# P3 c_q/c_kv rmsnorm loops: 4 rows in flight per wave (loads de-serialised), on top of the previous stack
# baseline (speedup 1.0000x reference)
; DI unsigned pk2(float lo, float hi) { const f32x2_t v = {lo, hi}; return __builtin_bit_cast(unsigned, __builtin_convertvector(v, bf16x2_t)); }
; DI void phase_norm_bf(bf16_t* x, int ncol, int gw, int ngw, int lane) {
;     const int nj = ncol / 128;
;     for (int r = gw; r < MC; r += ngw) {
;         unsigned* row = (unsigned*)(x + (size_t)r * ncol); unsigned w[3]; float ss = 0.f;
; #pragma unroll
;         for (int j = 0; j < 3; ++j) if (j < nj) { w[j] = row[j * 64 + lane]; const float a = bflo(w[j]), b = bfhi(w[j]); ss += a * a + b * b; }
;         ss = wave_sum(ss); const float rs = rsqrtf((ss + (float)ncol * EPS) * (ncol == 384 ? (1.0f / 384.0f) : (1.0f / 256.0f)));
; #pragma unroll
;         for (int j = 0; j < 3; ++j) if (j < nj) row[j * 64 + lane] = pk2(bflo(w[j]) * rs, bfhi(w[j]) * rs);
;     }
.Lcq_top:
	v_readfirstlane_b32 vcc_lo, v13
	s_add_u32 vcc_lo, vcc_lo, 0x960
	s_cmp_gt_i32 vcc_lo, s10
	s_cbranch_scc1 .Lcq_rem
	s_mov_b64 s[16:17], 0x96000
	v_lshl_add_u64 v[26:27], v[4:5], 0, s[16:17]
	v_lshl_add_u64 v[28:29], v[26:27], 0, s[16:17]
	v_lshl_add_u64 v[30:31], v[28:29], 0, s[16:17]
	global_load_dword v32, v[4:5], off offset:-256
	global_load_dword v33, v[4:5], off
	global_load_dword v34, v[4:5], off offset:256
	global_load_dword v35, v[26:27], off offset:-256
	global_load_dword v36, v[26:27], off
	global_load_dword v37, v[26:27], off offset:256
	global_load_dword v38, v[28:29], off offset:-256
	global_load_dword v39, v[28:29], off
	global_load_dword v40, v[28:29], off offset:256
	global_load_dword v41, v[30:31], off offset:-256
	global_load_dword v42, v[30:31], off
	global_load_dword v43, v[30:31], off offset:256
	s_waitcnt vmcnt(9)
	v_lshlrev_b32_e32 v44, 16, v32
	v_and_b32_e32 v45, 0xffff0000, v32
	v_lshlrev_b32_e32 v46, 16, v33
	v_and_b32_e32 v47, 0xffff0000, v33
	v_lshlrev_b32_e32 v48, 16, v34
	v_and_b32_e32 v49, 0xffff0000, v34
	v_mul_f32_e32 v68, v44, v44
	v_fmac_f32_e32 v68, v45, v45
	v_fmac_f32_e32 v68, v46, v46
	v_fmac_f32_e32 v68, v47, v47
	v_fmac_f32_e32 v68, v48, v48
	v_fmac_f32_e32 v68, v49, v49
	s_waitcnt vmcnt(6)
	v_lshlrev_b32_e32 v50, 16, v35
	v_and_b32_e32 v51, 0xffff0000, v35
	v_lshlrev_b32_e32 v52, 16, v36
	v_and_b32_e32 v53, 0xffff0000, v36
	v_lshlrev_b32_e32 v54, 16, v37
	v_and_b32_e32 v55, 0xffff0000, v37
	v_mul_f32_e32 v69, v50, v50
	v_fmac_f32_e32 v69, v51, v51
	v_fmac_f32_e32 v69, v52, v52
	v_fmac_f32_e32 v69, v53, v53
	v_fmac_f32_e32 v69, v54, v54
	v_fmac_f32_e32 v69, v55, v55
	s_waitcnt vmcnt(3)
	v_lshlrev_b32_e32 v56, 16, v38
	v_and_b32_e32 v57, 0xffff0000, v38
	v_lshlrev_b32_e32 v58, 16, v39
	v_and_b32_e32 v59, 0xffff0000, v39
	v_lshlrev_b32_e32 v60, 16, v40
	v_and_b32_e32 v61, 0xffff0000, v40
	v_mul_f32_e32 v70, v56, v56
	v_fmac_f32_e32 v70, v57, v57
	v_fmac_f32_e32 v70, v58, v58
	v_fmac_f32_e32 v70, v59, v59
	v_fmac_f32_e32 v70, v60, v60
	v_fmac_f32_e32 v70, v61, v61
	s_waitcnt vmcnt(0)
	v_lshlrev_b32_e32 v62, 16, v41
	v_and_b32_e32 v63, 0xffff0000, v41
	v_lshlrev_b32_e32 v64, 16, v42
	v_and_b32_e32 v65, 0xffff0000, v42
	v_lshlrev_b32_e32 v66, 16, v43
	v_and_b32_e32 v67, 0xffff0000, v43
	v_mul_f32_e32 v71, v62, v62
	v_fmac_f32_e32 v71, v63, v63
	v_fmac_f32_e32 v71, v64, v64
	v_fmac_f32_e32 v71, v65, v65
	v_fmac_f32_e32 v71, v66, v66
	v_fmac_f32_e32 v71, v67, v67
	ds_bpermute_b32 v72, v6, v68
	ds_bpermute_b32 v73, v6, v69
	ds_bpermute_b32 v74, v6, v70
	ds_bpermute_b32 v75, v6, v71
	s_waitcnt lgkmcnt(0)
	v_add_f32_e32 v68, v68, v72
	v_add_f32_e32 v69, v69, v73
	v_add_f32_e32 v70, v70, v74
	v_add_f32_e32 v71, v71, v75
	ds_bpermute_b32 v72, v7, v68
	ds_bpermute_b32 v73, v7, v69
	ds_bpermute_b32 v74, v7, v70
	ds_bpermute_b32 v75, v7, v71
	s_waitcnt lgkmcnt(0)
	v_add_f32_e32 v68, v68, v72
	v_add_f32_e32 v69, v69, v73
	v_add_f32_e32 v70, v70, v74
	v_add_f32_e32 v71, v71, v75
	ds_bpermute_b32 v72, v8, v68
	ds_bpermute_b32 v73, v8, v69
	ds_bpermute_b32 v74, v8, v70
	ds_bpermute_b32 v75, v8, v71
	s_waitcnt lgkmcnt(0)
	v_add_f32_e32 v68, v68, v72
	v_add_f32_e32 v69, v69, v73
	v_add_f32_e32 v70, v70, v74
	v_add_f32_e32 v71, v71, v75
	ds_bpermute_b32 v72, v9, v68
	ds_bpermute_b32 v73, v9, v69
	ds_bpermute_b32 v74, v9, v70
	ds_bpermute_b32 v75, v9, v71
	s_waitcnt lgkmcnt(0)
	v_add_f32_e32 v68, v68, v72
	v_add_f32_e32 v69, v69, v73
	v_add_f32_e32 v70, v70, v74
	v_add_f32_e32 v71, v71, v75
	ds_bpermute_b32 v72, v10, v68
	ds_bpermute_b32 v73, v10, v69
	ds_bpermute_b32 v74, v10, v70
	ds_bpermute_b32 v75, v10, v71
	s_waitcnt lgkmcnt(0)
	v_add_f32_e32 v68, v68, v72
	v_add_f32_e32 v69, v69, v73
	v_add_f32_e32 v70, v70, v74
	v_add_f32_e32 v71, v71, v75
	ds_bpermute_b32 v72, v11, v68
	ds_bpermute_b32 v73, v11, v69
	ds_bpermute_b32 v74, v11, v70
	ds_bpermute_b32 v75, v11, v71
	s_waitcnt lgkmcnt(0)
	v_add_f32_e32 v68, v68, v72
	v_add_f32_e32 v69, v69, v73
	v_add_f32_e32 v70, v70, v74
	v_add_f32_e32 v71, v71, v75
	v_add_f32_e32 v68, 0x39c9539c, v68
	v_mul_f32_e32 v68, 0x3b2aaaab, v68
	v_cmp_gt_f32_e32 vcc, s19, v68
	v_mul_f32_e32 v72, 0x4b800000, v68
	s_nop 0
	v_cndmask_b32_e32 v68, v68, v72, vcc
	v_rsq_f32_e32 v68, v68
	s_nop 0
	v_mul_f32_e32 v72, 0x45800000, v68
	v_cndmask_b32_e32 v76, v68, v72, vcc
	v_add_f32_e32 v69, 0x39c9539c, v69
	v_mul_f32_e32 v69, 0x3b2aaaab, v69
	v_cmp_gt_f32_e32 vcc, s19, v69
	v_mul_f32_e32 v72, 0x4b800000, v69
	s_nop 0
	v_cndmask_b32_e32 v69, v69, v72, vcc
	v_rsq_f32_e32 v69, v69
	s_nop 0
	v_mul_f32_e32 v72, 0x45800000, v69
	v_cndmask_b32_e32 v78, v69, v72, vcc
	v_add_f32_e32 v70, 0x39c9539c, v70
	v_mul_f32_e32 v70, 0x3b2aaaab, v70
	v_cmp_gt_f32_e32 vcc, s19, v70
	v_mul_f32_e32 v72, 0x4b800000, v70
	s_nop 0
	v_cndmask_b32_e32 v70, v70, v72, vcc
	v_rsq_f32_e32 v70, v70
	s_nop 0
	v_mul_f32_e32 v72, 0x45800000, v70
	v_cndmask_b32_e32 v80, v70, v72, vcc
	v_add_f32_e32 v71, 0x39c9539c, v71
	v_mul_f32_e32 v71, 0x3b2aaaab, v71
	v_cmp_gt_f32_e32 vcc, s19, v71
	v_mul_f32_e32 v72, 0x4b800000, v71
	s_nop 0
	v_cndmask_b32_e32 v71, v71, v72, vcc
	v_rsq_f32_e32 v71, v71
	s_nop 0
	v_mul_f32_e32 v72, 0x45800000, v71
	v_cndmask_b32_e32 v82, v71, v72, vcc
	v_pk_mul_f32 v[84:85], v[76:77], v[44:45] op_sel_hi:[0,1]
	v_cvt_pk_bf16_f32 v84, v84, v85
	global_store_dword v[4:5], v84, off offset:-256
	v_pk_mul_f32 v[84:85], v[76:77], v[46:47] op_sel_hi:[0,1]
	v_cvt_pk_bf16_f32 v84, v84, v85
	global_store_dword v[4:5], v84, off
	v_pk_mul_f32 v[84:85], v[76:77], v[48:49] op_sel_hi:[0,1]
	v_cvt_pk_bf16_f32 v84, v84, v85
	global_store_dword v[4:5], v84, off offset:256
	v_pk_mul_f32 v[84:85], v[78:79], v[50:51] op_sel_hi:[0,1]
	v_cvt_pk_bf16_f32 v84, v84, v85
	global_store_dword v[26:27], v84, off offset:-256
	v_pk_mul_f32 v[84:85], v[78:79], v[52:53] op_sel_hi:[0,1]
	v_cvt_pk_bf16_f32 v84, v84, v85
	global_store_dword v[26:27], v84, off
	v_pk_mul_f32 v[84:85], v[78:79], v[54:55] op_sel_hi:[0,1]
	v_cvt_pk_bf16_f32 v84, v84, v85
	global_store_dword v[26:27], v84, off offset:256
	v_pk_mul_f32 v[84:85], v[80:81], v[56:57] op_sel_hi:[0,1]
	v_cvt_pk_bf16_f32 v84, v84, v85
	global_store_dword v[28:29], v84, off offset:-256
	v_pk_mul_f32 v[84:85], v[80:81], v[58:59] op_sel_hi:[0,1]
	v_cvt_pk_bf16_f32 v84, v84, v85
	global_store_dword v[28:29], v84, off
	v_pk_mul_f32 v[84:85], v[80:81], v[60:61] op_sel_hi:[0,1]
	v_cvt_pk_bf16_f32 v84, v84, v85
	global_store_dword v[28:29], v84, off offset:256
	v_pk_mul_f32 v[84:85], v[82:83], v[62:63] op_sel_hi:[0,1]
	v_cvt_pk_bf16_f32 v84, v84, v85
	global_store_dword v[30:31], v84, off offset:-256
	v_pk_mul_f32 v[84:85], v[82:83], v[64:65] op_sel_hi:[0,1]
	v_cvt_pk_bf16_f32 v84, v84, v85
	global_store_dword v[30:31], v84, off
	v_pk_mul_f32 v[84:85], v[82:83], v[66:67] op_sel_hi:[0,1]
	v_cvt_pk_bf16_f32 v84, v84, v85
	global_store_dword v[30:31], v84, off offset:256
	v_add_u32_e32 v13, 0xc80, v13
	v_lshl_add_u64 v[4:5], v[30:31], 0, s[16:17]
	v_readfirstlane_b32 vcc_lo, v13
	s_cmp_gt_i32 vcc_lo, s10
	s_cbranch_scc1 .Lcq_done
	s_branch .Lcq_top
; DI unsigned pk2(float lo, float hi) { const f32x2_t v = {lo, hi}; return __builtin_bit_cast(unsigned, __builtin_convertvector(v, bf16x2_t)); }
; DI void phase_norm_bf(bf16_t* x, int ncol, int gw, int ngw, int lane) {
;     const int nj = ncol / 128;
;     for (int r = gw; r < MC; r += ngw) {
;         unsigned* row = (unsigned*)(x + (size_t)r * ncol); unsigned w[3]; float ss = 0.f;
; #pragma unroll
;         for (int j = 0; j < 3; ++j) if (j < nj) { w[j] = row[j * 64 + lane]; const float a = bflo(w[j]), b = bfhi(w[j]); ss += a * a + b * b; }
;         ss = wave_sum(ss); const float rs = rsqrtf((ss + (float)ncol * EPS) * (ncol == 384 ? (1.0f / 384.0f) : (1.0f / 256.0f)));
; #pragma unroll
;         for (int j = 0; j < 3; ++j) if (j < nj) row[j * 64 + lane] = pk2(bflo(w[j]) * rs, bfhi(w[j]) * rs);
;     }
; __global__ void __launch_bounds__(512, 2) mega(Params P) {
;     ...
;                 if (blk >= 156) { phase_norm_bf(WSP(bf16_t, WS_CQ), 384, (blk - 156) * 8 + wave, 100 * 8, lane); phase_norm_bf(WSP(bf16_t, WS_CKV), 256, (blk - 156) * 8 + wave, 100 * 8, lane); }
.Lcq_rem:
.LBB0_840:
	global_load_dword v15, v[4:5], off offset:-256
	global_load_dword v17, v[4:5], off
	global_load_dword v19, v[4:5], off offset:256
	v_add_u32_e32 v13, 0x320, v13
	s_mov_b64 s[16:17], 0x96000
	s_waitcnt vmcnt(0)
	v_lshlrev_b32_e32 v14, 16, v15
	v_and_b32_e32 v15, 0xffff0000, v15
	v_lshlrev_b32_e32 v18, 16, v19
	v_and_b32_e32 v19, 0xffff0000, v19
	v_lshlrev_b32_e32 v16, 16, v17
	v_and_b32_e32 v17, 0xffff0000, v17
	v_mov_b32_e32 v24, v15
	v_mov_b32_e32 v25, v19
	v_pk_mul_f32 v[20:21], v[16:17], v[16:17]
	v_mov_b32_e32 v22, v14
	v_mov_b32_e32 v23, v18
	v_pk_mul_f32 v[24:25], v[24:25], v[24:25]
	v_add_f32_e32 v20, v20, v21
	v_pk_fma_f32 v[22:23], v[22:23], v[22:23], v[24:25]
	s_nop 0
	v_add_f32_e32 v20, v22, v20
	v_add_f32_e32 v20, v20, v23
	ds_bpermute_b32 v21, v6, v20
	s_waitcnt lgkmcnt(0)
	v_add_f32_e32 v20, v20, v21
	ds_bpermute_b32 v21, v7, v20
	s_waitcnt lgkmcnt(0)
	v_add_f32_e32 v20, v20, v21
	ds_bpermute_b32 v21, v8, v20
	s_waitcnt lgkmcnt(0)
	v_add_f32_e32 v20, v20, v21
	ds_bpermute_b32 v21, v9, v20
	s_waitcnt lgkmcnt(0)
	v_add_f32_e32 v20, v20, v21
	ds_bpermute_b32 v21, v10, v20
	s_waitcnt lgkmcnt(0)
	v_add_f32_e32 v20, v20, v21
	ds_bpermute_b32 v21, v11, v20
	s_waitcnt lgkmcnt(0)
	v_add_f32_e32 v20, v20, v21
	v_add_f32_e32 v20, 0x39c9539c, v20
	v_mul_f32_e32 v20, 0x3b2aaaab, v20
	v_cmp_gt_f32_e32 vcc, s19, v20
	v_mul_f32_e32 v21, 0x4b800000, v20
	s_nop 0
	v_cndmask_b32_e32 v20, v20, v21, vcc
	v_rsq_f32_e32 v20, v20
	s_nop 0
	v_mul_f32_e32 v21, 0x45800000, v20
	v_cndmask_b32_e32 v20, v20, v21, vcc
	v_pk_mul_f32 v[14:15], v[20:21], v[14:15] op_sel_hi:[0,1]
	v_cvt_pk_bf16_f32 v14, v14, v15
	global_store_dword v[4:5], v14, off offset:-256
	v_pk_mul_f32 v[14:15], v[20:21], v[16:17] op_sel_hi:[0,1]
	v_cvt_pk_bf16_f32 v14, v14, v15
	global_store_dword v[4:5], v14, off
	v_pk_mul_f32 v[14:15], v[20:21], v[18:19] op_sel_hi:[0,1]
	v_cvt_pk_bf16_f32 v14, v14, v15
	v_cmp_lt_i32_e32 vcc, s10, v13
	global_store_dword v[4:5], v14, off offset:256
	v_lshl_add_u64 v[4:5], v[4:5], 0, s[16:17]
	s_or_b64 s[8:9], vcc, s[8:9]
	s_andn2_b64 exec, exec, s[8:9]
	s_cbranch_execnz .LBB0_840
.Lcq_done:
	s_or_b64 exec, exec, s[8:9]
	v_readlane_b32 s0, v254, 28
	v_lshlrev_b64 v[0:1], 9, v[0:1]
	s_add_u32 s8, s0, s14
	v_readlane_b32 s0, v254, 33
	v_or_b32_e32 v0, v0, v2
	s_addc_u32 s9, s0, s2
	v_lshl_add_u64 v[0:1], s[8:9], 0, v[0:1]
	s_mov_b64 s[8:9], 0
.Lckv_top:
	v_readfirstlane_b32 vcc_lo, v12
	s_add_u32 vcc_lo, vcc_lo, 0x960
	s_cmp_gt_i32 vcc_lo, s10
	s_cbranch_scc1 .Lckv_rem
	s_mov_b64 s[16:17], 0x64000
	v_lshl_add_u64 v[26:27], v[0:1], 0, s[16:17]
	v_lshl_add_u64 v[28:29], v[26:27], 0, s[16:17]
	v_lshl_add_u64 v[30:31], v[28:29], 0, s[16:17]
	global_load_dword v32, v[0:1], off
	global_load_dword v33, v[0:1], off offset:256
	global_load_dword v34, v[26:27], off
	global_load_dword v35, v[26:27], off offset:256
	global_load_dword v36, v[28:29], off
	global_load_dword v37, v[28:29], off offset:256
	global_load_dword v38, v[30:31], off
	global_load_dword v39, v[30:31], off offset:256
	s_waitcnt vmcnt(6)
	v_lshlrev_b32_e32 v44, 16, v32
	v_and_b32_e32 v45, 0xffff0000, v32
	v_lshlrev_b32_e32 v46, 16, v33
	v_and_b32_e32 v47, 0xffff0000, v33
	v_mul_f32_e32 v68, v44, v44
	v_fmac_f32_e32 v68, v45, v45
	v_fmac_f32_e32 v68, v46, v46
	v_fmac_f32_e32 v68, v47, v47
	s_waitcnt vmcnt(4)
	v_lshlrev_b32_e32 v48, 16, v34
	v_and_b32_e32 v49, 0xffff0000, v34
	v_lshlrev_b32_e32 v50, 16, v35
	v_and_b32_e32 v51, 0xffff0000, v35
	v_mul_f32_e32 v69, v48, v48
	v_fmac_f32_e32 v69, v49, v49
	v_fmac_f32_e32 v69, v50, v50
	v_fmac_f32_e32 v69, v51, v51
	s_waitcnt vmcnt(2)
	v_lshlrev_b32_e32 v52, 16, v36
	v_and_b32_e32 v53, 0xffff0000, v36
	v_lshlrev_b32_e32 v54, 16, v37
	v_and_b32_e32 v55, 0xffff0000, v37
	v_mul_f32_e32 v70, v52, v52
	v_fmac_f32_e32 v70, v53, v53
	v_fmac_f32_e32 v70, v54, v54
	v_fmac_f32_e32 v70, v55, v55
	s_waitcnt vmcnt(0)
	v_lshlrev_b32_e32 v56, 16, v38
	v_and_b32_e32 v57, 0xffff0000, v38
	v_lshlrev_b32_e32 v58, 16, v39
	v_and_b32_e32 v59, 0xffff0000, v39
	v_mul_f32_e32 v71, v56, v56
	v_fmac_f32_e32 v71, v57, v57
	v_fmac_f32_e32 v71, v58, v58
	v_fmac_f32_e32 v71, v59, v59
	ds_bpermute_b32 v72, v6, v68
	ds_bpermute_b32 v73, v6, v69
	ds_bpermute_b32 v74, v6, v70
	ds_bpermute_b32 v75, v6, v71
	s_waitcnt lgkmcnt(0)
	v_add_f32_e32 v68, v68, v72
	v_add_f32_e32 v69, v69, v73
	v_add_f32_e32 v70, v70, v74
	v_add_f32_e32 v71, v71, v75
	ds_bpermute_b32 v72, v7, v68
	ds_bpermute_b32 v73, v7, v69
	ds_bpermute_b32 v74, v7, v70
	ds_bpermute_b32 v75, v7, v71
	s_waitcnt lgkmcnt(0)
	v_add_f32_e32 v68, v68, v72
	v_add_f32_e32 v69, v69, v73
	v_add_f32_e32 v70, v70, v74
	v_add_f32_e32 v71, v71, v75
	ds_bpermute_b32 v72, v8, v68
	ds_bpermute_b32 v73, v8, v69
	ds_bpermute_b32 v74, v8, v70
	ds_bpermute_b32 v75, v8, v71
	s_waitcnt lgkmcnt(0)
	v_add_f32_e32 v68, v68, v72
	v_add_f32_e32 v69, v69, v73
	v_add_f32_e32 v70, v70, v74
	v_add_f32_e32 v71, v71, v75
	ds_bpermute_b32 v72, v9, v68
	ds_bpermute_b32 v73, v9, v69
	ds_bpermute_b32 v74, v9, v70
	ds_bpermute_b32 v75, v9, v71
	s_waitcnt lgkmcnt(0)
; DI unsigned pk2(float lo, float hi) { const f32x2_t v = {lo, hi}; return __builtin_bit_cast(unsigned, __builtin_convertvector(v, bf16x2_t)); }
; DI void phase_norm_bf(bf16_t* x, int ncol, int gw, int ngw, int lane) {
;     const int nj = ncol / 128;
;     for (int r = gw; r < MC; r += ngw) {
;         unsigned* row = (unsigned*)(x + (size_t)r * ncol); unsigned w[3]; float ss = 0.f;
; #pragma unroll
;         for (int j = 0; j < 3; ++j) if (j < nj) { w[j] = row[j * 64 + lane]; const float a = bflo(w[j]), b = bfhi(w[j]); ss += a * a + b * b; }
;         ss = wave_sum(ss); const float rs = rsqrtf((ss + (float)ncol * EPS) * (ncol == 384 ? (1.0f / 384.0f) : (1.0f / 256.0f)));
; #pragma unroll
;         for (int j = 0; j < 3; ++j) if (j < nj) row[j * 64 + lane] = pk2(bflo(w[j]) * rs, bfhi(w[j]) * rs);
;     }
	v_add_f32_e32 v68, v68, v72
	v_add_f32_e32 v69, v69, v73
	v_add_f32_e32 v70, v70, v74
	v_add_f32_e32 v71, v71, v75
	ds_bpermute_b32 v72, v10, v68
	ds_bpermute_b32 v73, v10, v69
	ds_bpermute_b32 v74, v10, v70
	ds_bpermute_b32 v75, v10, v71
	s_waitcnt lgkmcnt(0)
	v_add_f32_e32 v68, v68, v72
	v_add_f32_e32 v69, v69, v73
	v_add_f32_e32 v70, v70, v74
	v_add_f32_e32 v71, v71, v75
	ds_bpermute_b32 v72, v11, v68
	ds_bpermute_b32 v73, v11, v69
	ds_bpermute_b32 v74, v11, v70
	ds_bpermute_b32 v75, v11, v71
	s_waitcnt lgkmcnt(0)
	v_add_f32_e32 v68, v68, v72
	v_add_f32_e32 v69, v69, v73
	v_add_f32_e32 v70, v70, v74
	v_add_f32_e32 v71, v71, v75
	v_add_f32_e32 v68, 0x398637bd, v68
	v_mul_f32_e32 v68, 0x3b800000, v68
	v_cmp_gt_f32_e32 vcc, s19, v68
	v_mul_f32_e32 v72, 0x4b800000, v68
	s_nop 0
	v_cndmask_b32_e32 v68, v68, v72, vcc
	v_rsq_f32_e32 v68, v68
	s_nop 0
	v_mul_f32_e32 v72, 0x45800000, v68
	v_cndmask_b32_e32 v76, v68, v72, vcc
	v_add_f32_e32 v69, 0x398637bd, v69
	v_mul_f32_e32 v69, 0x3b800000, v69
	v_cmp_gt_f32_e32 vcc, s19, v69
	v_mul_f32_e32 v72, 0x4b800000, v69
	s_nop 0
	v_cndmask_b32_e32 v69, v69, v72, vcc
	v_rsq_f32_e32 v69, v69
	s_nop 0
	v_mul_f32_e32 v72, 0x45800000, v69
	v_cndmask_b32_e32 v78, v69, v72, vcc
	v_add_f32_e32 v70, 0x398637bd, v70
	v_mul_f32_e32 v70, 0x3b800000, v70
	v_cmp_gt_f32_e32 vcc, s19, v70
	v_mul_f32_e32 v72, 0x4b800000, v70
	s_nop 0
	v_cndmask_b32_e32 v70, v70, v72, vcc
	v_rsq_f32_e32 v70, v70
	s_nop 0
	v_mul_f32_e32 v72, 0x45800000, v70
	v_cndmask_b32_e32 v80, v70, v72, vcc
	v_add_f32_e32 v71, 0x398637bd, v71
	v_mul_f32_e32 v71, 0x3b800000, v71
	v_cmp_gt_f32_e32 vcc, s19, v71
	v_mul_f32_e32 v72, 0x4b800000, v71
	s_nop 0
	v_cndmask_b32_e32 v71, v71, v72, vcc
	v_rsq_f32_e32 v71, v71
	s_nop 0
	v_mul_f32_e32 v72, 0x45800000, v71
	v_cndmask_b32_e32 v82, v71, v72, vcc
	v_pk_mul_f32 v[84:85], v[76:77], v[44:45] op_sel_hi:[0,1]
	v_cvt_pk_bf16_f32 v84, v84, v85
	global_store_dword v[0:1], v84, off
	v_pk_mul_f32 v[84:85], v[76:77], v[46:47] op_sel_hi:[0,1]
	v_cvt_pk_bf16_f32 v84, v84, v85
	global_store_dword v[0:1], v84, off offset:256
	v_pk_mul_f32 v[84:85], v[78:79], v[48:49] op_sel_hi:[0,1]
	v_cvt_pk_bf16_f32 v84, v84, v85
	global_store_dword v[26:27], v84, off
	v_pk_mul_f32 v[84:85], v[78:79], v[50:51] op_sel_hi:[0,1]
	v_cvt_pk_bf16_f32 v84, v84, v85
	global_store_dword v[26:27], v84, off offset:256
	v_pk_mul_f32 v[84:85], v[80:81], v[52:53] op_sel_hi:[0,1]
	v_cvt_pk_bf16_f32 v84, v84, v85
	global_store_dword v[28:29], v84, off
	v_pk_mul_f32 v[84:85], v[80:81], v[54:55] op_sel_hi:[0,1]
	v_cvt_pk_bf16_f32 v84, v84, v85
	global_store_dword v[28:29], v84, off offset:256
	v_pk_mul_f32 v[84:85], v[82:83], v[56:57] op_sel_hi:[0,1]
	v_cvt_pk_bf16_f32 v84, v84, v85
	global_store_dword v[30:31], v84, off
	v_pk_mul_f32 v[84:85], v[82:83], v[58:59] op_sel_hi:[0,1]
	v_cvt_pk_bf16_f32 v84, v84, v85
	global_store_dword v[30:31], v84, off offset:256
	v_add_u32_e32 v12, 0xc80, v12
	v_lshl_add_u64 v[0:1], v[30:31], 0, s[16:17]
	v_readfirstlane_b32 vcc_lo, v12
	s_cmp_gt_i32 vcc_lo, s10
	s_cbranch_scc1 .LBB0_843
	s_branch .Lckv_top
.Lckv_rem:
.LBB0_842:
	global_load_dword v2, v[0:1], off
	v_add_u32_e32 v12, 0x320, v12
	s_mov_b64 s[16:17], 0x64000
	s_waitcnt vmcnt(0)
	v_lshlrev_b32_e32 v4, 16, v2
	v_and_b32_e32 v5, 0xffff0000, v2
	global_load_dword v2, v[0:1], off offset:256
	v_mov_b32_e32 v18, v5
	v_mov_b32_e32 v16, v4
	s_waitcnt vmcnt(0)
	v_and_b32_e32 v15, 0xffff0000, v2
	v_lshlrev_b32_e32 v14, 16, v2
	v_mov_b32_e32 v19, v15
	v_mov_b32_e32 v17, v14
	v_pk_mul_f32 v[18:19], v[18:19], v[18:19]
	s_nop 0
	v_pk_fma_f32 v[16:17], v[16:17], v[16:17], v[18:19]
	s_nop 0
	v_add_f32_e32 v2, v16, v17
	ds_bpermute_b32 v13, v6, v2
	s_waitcnt lgkmcnt(0)
	v_add_f32_e32 v2, v2, v13
	ds_bpermute_b32 v13, v7, v2
	s_waitcnt lgkmcnt(0)
	v_add_f32_e32 v2, v2, v13
	ds_bpermute_b32 v13, v8, v2
	s_waitcnt lgkmcnt(0)
	v_add_f32_e32 v2, v2, v13
	ds_bpermute_b32 v13, v9, v2
	s_waitcnt lgkmcnt(0)
	v_add_f32_e32 v2, v2, v13
	ds_bpermute_b32 v13, v10, v2
	s_waitcnt lgkmcnt(0)
	v_add_f32_e32 v2, v2, v13
	ds_bpermute_b32 v13, v11, v2
	s_waitcnt lgkmcnt(0)
	v_add_f32_e32 v2, v2, v13
	v_add_f32_e32 v2, 0x398637bd, v2
	v_mul_f32_e32 v2, 0x3b800000, v2
	v_cmp_gt_f32_e32 vcc, s19, v2
	v_mul_f32_e32 v13, 0x4b800000, v2
	s_nop 0
	v_cndmask_b32_e32 v2, v2, v13, vcc
	v_rsq_f32_e32 v2, v2
	s_nop 0
	v_mul_f32_e32 v13, 0x45800000, v2
	v_cndmask_b32_e32 v2, v2, v13, vcc
	v_pk_mul_f32 v[4:5], v[2:3], v[4:5] op_sel_hi:[0,1]
	v_cvt_pk_bf16_f32 v4, v4, v5
	global_store_dword v[0:1], v4, off
	v_pk_mul_f32 v[4:5], v[2:3], v[14:15] op_sel_hi:[0,1]
	v_cvt_pk_bf16_f32 v2, v4, v5
	v_cmp_lt_i32_e32 vcc, s10, v12
	global_store_dword v[0:1], v2, off offset:256
	v_lshl_add_u64 v[0:1], v[0:1], 0, s[16:17]
	s_or_b64 s[8:9], vcc, s[8:9]
	s_andn2_b64 exec, exec, s[8:9]
	s_cbranch_execnz .LBB0_842
